# P4 item loop: static s_setprio 1 for waves 4-7 (reset at P4 exit), on top of v047
# baseline (speedup 1.0000x reference)
.LBB0_818:
	v_readlane_b32 s8, v254, 2
	s_nop 3
	s_cmp_ge_u32 s8, 4
	s_cbranch_scc0 .Lp4_prio_done
	s_setprio 1

.LBB0_883:
	s_setprio 0
	v_readlane_b32 s44, v254, 3
	v_readlane_b32 s0, v254, 51
	v_readlane_b32 s45, v254, 4
	v_readlane_b32 s1, v254, 52
